# v25 + 256-byte alignment of the big GEMM K-loop heads
# baseline (speedup 1.0000x reference)
.LBB0_421:
	s_ashr_i32 s21, s20, 31
	s_lshl_b64 s[22:23], s[20:21], 15
	v_readlane_b32 s9, v245, 12
	s_add_u32 s22, s9, s22
	v_readlane_b32 s9, v245, 13
	s_addc_u32 s23, s9, s23
	s_and_b64 s[24:25], s[6:7], exec
	s_cselect_b32 s9, s23, s31
	s_cselect_b32 s21, s22, s30
	s_ashr_i32 s19, s18, 31
	s_lshl_b64 s[24:25], s[18:19], 15
	s_add_u32 s24, s4, s24
	s_addc_u32 s25, s5, s25
	s_and_b64 s[34:35], s[6:7], exec
	s_cselect_b32 s19, s25, s29
	s_cselect_b32 s50, s24, s28
	s_add_u32 s51, s28, 0x700000
	s_addc_u32 s52, s29, 0
	s_add_u32 s28, s30, 0x104000
	v_mov_b32_e32 v2, 0
	s_addc_u32 s29, s31, 0
	s_mov_b32 s53, -2
	v_mov_b32_e32 v3, v2
	v_mov_b32_e32 v4, v2
	v_mov_b32_e32 v5, v2
	v_mov_b32_e32 v6, v2
	v_mov_b32_e32 v7, v2
	v_mov_b32_e32 v8, v2
	v_mov_b32_e32 v9, v2
	v_mov_b32_e32 v18, v2
	v_mov_b32_e32 v19, v2
	v_mov_b32_e32 v20, v2
	v_mov_b32_e32 v21, v2
	v_mov_b32_e32 v22, v2
	v_mov_b32_e32 v23, v2
	v_mov_b32_e32 v24, v2
	v_mov_b32_e32 v25, v2
	s_waitcnt vmcnt(0)
	v_mov_b32_e32 v34, v2
	v_mov_b32_e32 v35, v2
	v_mov_b32_e32 v36, v2
	v_mov_b32_e32 v37, v2
	v_mov_b32_e32 v38, v2
	v_mov_b32_e32 v39, v2
	v_mov_b32_e32 v40, v2
	v_mov_b32_e32 v41, v2
	v_mov_b32_e32 v50, v2
	v_mov_b32_e32 v51, v2
	v_mov_b32_e32 v52, v2
	v_mov_b32_e32 v53, v2
	v_mov_b32_e32 v54, v2
	v_mov_b32_e32 v55, v2
	v_mov_b32_e32 v56, v2
	v_mov_b32_e32 v57, v2
	v_mov_b32_e32 v10, v2
	v_mov_b32_e32 v11, v2
	v_mov_b32_e32 v12, v2
	v_mov_b32_e32 v13, v2
	v_mov_b32_e32 v14, v2
	v_mov_b32_e32 v15, v2
	v_mov_b32_e32 v16, v2
	v_mov_b32_e32 v17, v2
	v_mov_b32_e32 v26, v2
	v_mov_b32_e32 v27, v2
	v_mov_b32_e32 v28, v2
	v_mov_b32_e32 v29, v2
	v_mov_b32_e32 v30, v2
	v_mov_b32_e32 v31, v2
	v_mov_b32_e32 v32, v2
	v_mov_b32_e32 v33, v2
	v_mov_b32_e32 v42, v2
	v_mov_b32_e32 v43, v2
	v_mov_b32_e32 v44, v2
	v_mov_b32_e32 v45, v2
	v_mov_b32_e32 v46, v2
	v_mov_b32_e32 v47, v2
	v_mov_b32_e32 v48, v2
	v_mov_b32_e32 v49, v2
	v_mov_b32_e32 v58, v2
	v_mov_b32_e32 v59, v2
	v_mov_b32_e32 v60, v2
	v_mov_b32_e32 v61, v2
	v_mov_b32_e32 v62, v2
	v_mov_b32_e32 v63, v2
	v_mov_b32_e32 v64, v2
	v_mov_b32_e32 v65, v2
	v_mov_b32_e32 v66, v2
	v_mov_b32_e32 v67, v2
	v_mov_b32_e32 v68, v2
	v_mov_b32_e32 v69, v2
	v_mov_b32_e32 v70, v2
	v_mov_b32_e32 v71, v2
	v_mov_b32_e32 v72, v2
	v_mov_b32_e32 v73, v2
	v_mov_b32_e32 v82, v2
	v_mov_b32_e32 v83, v2
	v_mov_b32_e32 v84, v2
	v_mov_b32_e32 v85, v2
	v_mov_b32_e32 v86, v2
	v_mov_b32_e32 v87, v2
	v_mov_b32_e32 v88, v2
	v_mov_b32_e32 v89, v2
	v_mov_b32_e32 v98, v2
	v_mov_b32_e32 v99, v2
	v_mov_b32_e32 v100, v2
	v_mov_b32_e32 v101, v2
	v_mov_b32_e32 v102, v2
	v_mov_b32_e32 v103, v2
	v_mov_b32_e32 v104, v2
	v_mov_b32_e32 v105, v2
	v_mov_b32_e32 v114, v2
	v_mov_b32_e32 v115, v2
	v_mov_b32_e32 v116, v2
	v_mov_b32_e32 v117, v2
	v_mov_b32_e32 v118, v2
	v_mov_b32_e32 v119, v2
	v_mov_b32_e32 v120, v2
	v_mov_b32_e32 v121, v2
	v_mov_b32_e32 v74, v2
	v_mov_b32_e32 v75, v2
	v_mov_b32_e32 v76, v2
	v_mov_b32_e32 v77, v2
	v_mov_b32_e32 v78, v2
	v_mov_b32_e32 v79, v2
	v_mov_b32_e32 v80, v2
	v_mov_b32_e32 v81, v2
	v_mov_b32_e32 v90, v2
	v_mov_b32_e32 v91, v2
	v_mov_b32_e32 v92, v2
	v_mov_b32_e32 v93, v2
	v_mov_b32_e32 v94, v2
	v_mov_b32_e32 v95, v2
	v_mov_b32_e32 v96, v2
	v_mov_b32_e32 v97, v2
	v_mov_b32_e32 v106, v2
	v_mov_b32_e32 v107, v2
	v_mov_b32_e32 v108, v2
	v_mov_b32_e32 v109, v2
	v_mov_b32_e32 v110, v2
	v_mov_b32_e32 v111, v2
	v_mov_b32_e32 v112, v2
	v_mov_b32_e32 v113, v2
	v_mov_b32_e32 v122, v2
	v_mov_b32_e32 v123, v2
	v_mov_b32_e32 v124, v2
	v_mov_b32_e32 v125, v2
	v_mov_b32_e32 v126, v2
	v_mov_b32_e32 v127, v2
	v_mov_b32_e32 v128, v2
	v_mov_b32_e32 v129, v2
	.p2align	8

.LBB0_500:
	s_ashr_i32 s21, s20, 31
	s_lshl_b64 s[22:23], s[20:21], 15
	v_readlane_b32 s24, v245, 14
	v_readlane_b32 s25, v245, 15
	s_add_u32 s22, s24, s22
	s_addc_u32 s23, s25, s23
	s_and_b64 s[24:25], s[6:7], exec
	s_cselect_b32 s5, s23, s27
	s_cselect_b32 s21, s22, s26
	s_ashr_i32 s19, s18, 31
	s_lshl_b64 s[24:25], s[18:19], 15
	v_readlane_b32 s28, v245, 8
	v_readlane_b32 s29, v245, 9
	s_add_u32 s24, s28, s24
	s_addc_u32 s25, s29, s25
	s_and_b64 s[28:29], s[6:7], exec
	s_cselect_b32 s19, s25, s11
	s_cselect_b32 s44, s24, s10
	s_add_u32 s45, s10, 0x100000
	s_addc_u32 s46, s11, 0
	s_add_u32 s10, s26, 0x104000
	v_mov_b32_e32 v2, 0
	s_addc_u32 s11, s27, 0
	s_mov_b32 s47, -2
	v_mov_b32_e32 v3, v2
	v_mov_b32_e32 v4, v2
	v_mov_b32_e32 v5, v2
	v_mov_b32_e32 v6, v2
	s_waitcnt lgkmcnt(0)
	v_mov_b32_e32 v7, v2
	v_mov_b32_e32 v8, v2
	v_mov_b32_e32 v9, v2
	v_mov_b32_e32 v18, v2
	v_mov_b32_e32 v19, v2
	v_mov_b32_e32 v20, v2
	v_mov_b32_e32 v21, v2
	v_mov_b32_e32 v22, v2
	v_mov_b32_e32 v23, v2
	v_mov_b32_e32 v24, v2
	v_mov_b32_e32 v25, v2
	v_mov_b32_e32 v34, v2
	v_mov_b32_e32 v35, v2
	v_mov_b32_e32 v36, v2
	v_mov_b32_e32 v37, v2
	v_mov_b32_e32 v38, v2
	v_mov_b32_e32 v39, v2
	v_mov_b32_e32 v40, v2
	v_mov_b32_e32 v41, v2
	v_mov_b32_e32 v50, v2
	v_mov_b32_e32 v51, v2
	v_mov_b32_e32 v52, v2
	v_mov_b32_e32 v53, v2
	v_mov_b32_e32 v54, v2
	v_mov_b32_e32 v55, v2
	v_mov_b32_e32 v56, v2
	v_mov_b32_e32 v57, v2
	v_mov_b32_e32 v10, v2
	v_mov_b32_e32 v11, v2
	v_mov_b32_e32 v12, v2
	v_mov_b32_e32 v13, v2
	v_mov_b32_e32 v14, v2
	v_mov_b32_e32 v15, v2
	v_mov_b32_e32 v16, v2
	v_mov_b32_e32 v17, v2
	v_mov_b32_e32 v26, v2
	v_mov_b32_e32 v27, v2
	v_mov_b32_e32 v28, v2
	v_mov_b32_e32 v29, v2
	v_mov_b32_e32 v30, v2
	v_mov_b32_e32 v31, v2
	v_mov_b32_e32 v32, v2
	v_mov_b32_e32 v33, v2
	v_mov_b32_e32 v42, v2
	v_mov_b32_e32 v43, v2
	v_mov_b32_e32 v44, v2
	v_mov_b32_e32 v45, v2
	v_mov_b32_e32 v46, v2
	v_mov_b32_e32 v47, v2
	v_mov_b32_e32 v48, v2
	v_mov_b32_e32 v49, v2
	v_mov_b32_e32 v58, v2
	v_mov_b32_e32 v59, v2
	v_mov_b32_e32 v60, v2
	v_mov_b32_e32 v61, v2
	v_mov_b32_e32 v62, v2
	v_mov_b32_e32 v63, v2
	v_mov_b32_e32 v64, v2
	v_mov_b32_e32 v65, v2
	v_mov_b32_e32 v66, v2
	v_mov_b32_e32 v67, v2
	v_mov_b32_e32 v68, v2
	v_mov_b32_e32 v69, v2
	v_mov_b32_e32 v70, v2
	v_mov_b32_e32 v71, v2
	v_mov_b32_e32 v72, v2
	v_mov_b32_e32 v73, v2
	v_mov_b32_e32 v82, v2
	v_mov_b32_e32 v83, v2
	v_mov_b32_e32 v84, v2
	v_mov_b32_e32 v85, v2
	v_mov_b32_e32 v86, v2
	v_mov_b32_e32 v87, v2
	v_mov_b32_e32 v88, v2
	v_mov_b32_e32 v89, v2
	v_mov_b32_e32 v98, v2
	v_mov_b32_e32 v99, v2
	v_mov_b32_e32 v100, v2
	v_mov_b32_e32 v101, v2
	v_mov_b32_e32 v102, v2
	v_mov_b32_e32 v103, v2
	v_mov_b32_e32 v104, v2
	v_mov_b32_e32 v105, v2
	v_mov_b32_e32 v114, v2
	v_mov_b32_e32 v115, v2
	v_mov_b32_e32 v116, v2
	v_mov_b32_e32 v117, v2
	v_mov_b32_e32 v118, v2
	v_mov_b32_e32 v119, v2
	v_mov_b32_e32 v120, v2
	v_mov_b32_e32 v121, v2
	v_mov_b32_e32 v74, v2
	v_mov_b32_e32 v75, v2
	v_mov_b32_e32 v76, v2
	v_mov_b32_e32 v77, v2
	v_mov_b32_e32 v78, v2
	v_mov_b32_e32 v79, v2
	v_mov_b32_e32 v80, v2
	v_mov_b32_e32 v81, v2
	v_mov_b32_e32 v90, v2
	v_mov_b32_e32 v91, v2
	v_mov_b32_e32 v92, v2
	v_mov_b32_e32 v93, v2
	v_mov_b32_e32 v94, v2
	v_mov_b32_e32 v95, v2
	v_mov_b32_e32 v96, v2
	v_mov_b32_e32 v97, v2
	v_mov_b32_e32 v106, v2
	v_mov_b32_e32 v107, v2
	v_mov_b32_e32 v108, v2
	v_mov_b32_e32 v109, v2
	v_mov_b32_e32 v110, v2
	v_mov_b32_e32 v111, v2
	v_mov_b32_e32 v112, v2
	v_mov_b32_e32 v113, v2
	v_mov_b32_e32 v122, v2
	v_mov_b32_e32 v123, v2
	v_mov_b32_e32 v124, v2
	v_mov_b32_e32 v125, v2
	v_mov_b32_e32 v126, v2
	v_mov_b32_e32 v127, v2
	v_mov_b32_e32 v128, v2
	v_mov_b32_e32 v129, v2
	.p2align	8

.LBB0_800:
	s_ashr_i32 s21, s20, 31
	s_lshl_b64 s[22:23], s[20:21], 15
	v_readlane_b32 s3, v245, 12
	s_add_u32 s22, s3, s22
	v_readlane_b32 s3, v245, 13
	s_addc_u32 s23, s3, s23
	s_and_b64 s[24:25], s[10:11], exec
	s_cselect_b32 s3, s23, s27
	s_cselect_b32 s5, s22, s26
	s_ashr_i32 s19, s18, 31
	s_lshl_b64 s[24:25], s[18:19], 15
	v_readlane_b32 s28, v245, 6
	v_readlane_b32 s29, v245, 7
	s_add_u32 s24, s28, s24
	s_addc_u32 s25, s29, s25
	s_and_b64 s[28:29], s[10:11], exec
	s_cselect_b32 s19, s25, s13
	s_cselect_b32 s21, s24, s12
	s_add_u32 s45, s12, 0x300000
	s_addc_u32 s46, s13, 0
	s_add_u32 s12, s26, 0x104000
	v_mov_b32_e32 v2, 0
	s_addc_u32 s13, s27, 0
	s_mov_b32 s47, -2
	v_mov_b32_e32 v3, v2
	v_mov_b32_e32 v4, v2
	v_mov_b32_e32 v5, v2
	v_mov_b32_e32 v6, v2
	v_mov_b32_e32 v7, v2
	v_mov_b32_e32 v8, v2
	v_mov_b32_e32 v9, v2
	v_mov_b32_e32 v18, v2
	v_mov_b32_e32 v19, v2
	v_mov_b32_e32 v20, v2
	v_mov_b32_e32 v21, v2
	v_mov_b32_e32 v22, v2
	v_mov_b32_e32 v23, v2
	v_mov_b32_e32 v24, v2
	v_mov_b32_e32 v25, v2
	s_waitcnt vmcnt(0)
	v_mov_b32_e32 v34, v2
	v_mov_b32_e32 v35, v2
	v_mov_b32_e32 v36, v2
	v_mov_b32_e32 v37, v2
	v_mov_b32_e32 v38, v2
	v_mov_b32_e32 v39, v2
	v_mov_b32_e32 v40, v2
	v_mov_b32_e32 v41, v2
	v_mov_b32_e32 v50, v2
	v_mov_b32_e32 v51, v2
	v_mov_b32_e32 v52, v2
	v_mov_b32_e32 v53, v2
	v_mov_b32_e32 v54, v2
	v_mov_b32_e32 v55, v2
	v_mov_b32_e32 v56, v2
	v_mov_b32_e32 v57, v2
	v_mov_b32_e32 v10, v2
	v_mov_b32_e32 v11, v2
	v_mov_b32_e32 v12, v2
	v_mov_b32_e32 v13, v2
	v_mov_b32_e32 v14, v2
	v_mov_b32_e32 v15, v2
	v_mov_b32_e32 v16, v2
	v_mov_b32_e32 v17, v2
	v_mov_b32_e32 v26, v2
	v_mov_b32_e32 v27, v2
	v_mov_b32_e32 v28, v2
	v_mov_b32_e32 v29, v2
	v_mov_b32_e32 v30, v2
	v_mov_b32_e32 v31, v2
	v_mov_b32_e32 v32, v2
	v_mov_b32_e32 v33, v2
	v_mov_b32_e32 v42, v2
	v_mov_b32_e32 v43, v2
	v_mov_b32_e32 v44, v2
	v_mov_b32_e32 v45, v2
	v_mov_b32_e32 v46, v2
	v_mov_b32_e32 v47, v2
	v_mov_b32_e32 v48, v2
	v_mov_b32_e32 v49, v2
	v_mov_b32_e32 v58, v2
	v_mov_b32_e32 v59, v2
	v_mov_b32_e32 v60, v2
	v_mov_b32_e32 v61, v2
	v_mov_b32_e32 v62, v2
	v_mov_b32_e32 v63, v2
	v_mov_b32_e32 v64, v2
	v_mov_b32_e32 v65, v2
	v_mov_b32_e32 v66, v2
	v_mov_b32_e32 v67, v2
	v_mov_b32_e32 v68, v2
	v_mov_b32_e32 v69, v2
	v_mov_b32_e32 v70, v2
	v_mov_b32_e32 v71, v2
	v_mov_b32_e32 v72, v2
	v_mov_b32_e32 v73, v2
	v_mov_b32_e32 v82, v2
	v_mov_b32_e32 v83, v2
	v_mov_b32_e32 v84, v2
	v_mov_b32_e32 v85, v2
	v_mov_b32_e32 v86, v2
	v_mov_b32_e32 v87, v2
	v_mov_b32_e32 v88, v2
	v_mov_b32_e32 v89, v2
	v_mov_b32_e32 v98, v2
	v_mov_b32_e32 v99, v2
	v_mov_b32_e32 v100, v2
	v_mov_b32_e32 v101, v2
	v_mov_b32_e32 v102, v2
	v_mov_b32_e32 v103, v2
	v_mov_b32_e32 v104, v2
	v_mov_b32_e32 v105, v2
	v_mov_b32_e32 v114, v2
	v_mov_b32_e32 v115, v2
	v_mov_b32_e32 v116, v2
	v_mov_b32_e32 v117, v2
	v_mov_b32_e32 v118, v2
	v_mov_b32_e32 v119, v2
	v_mov_b32_e32 v120, v2
	v_mov_b32_e32 v121, v2
	v_mov_b32_e32 v74, v2
	v_mov_b32_e32 v75, v2
	v_mov_b32_e32 v76, v2
	v_mov_b32_e32 v77, v2
	v_mov_b32_e32 v78, v2
	v_mov_b32_e32 v79, v2
	v_mov_b32_e32 v80, v2
	v_mov_b32_e32 v81, v2
	v_mov_b32_e32 v90, v2
	v_mov_b32_e32 v91, v2
	v_mov_b32_e32 v92, v2
	v_mov_b32_e32 v93, v2
	v_mov_b32_e32 v94, v2
	v_mov_b32_e32 v95, v2
	v_mov_b32_e32 v96, v2
	v_mov_b32_e32 v97, v2
	v_mov_b32_e32 v106, v2
	v_mov_b32_e32 v107, v2
	v_mov_b32_e32 v108, v2
	v_mov_b32_e32 v109, v2
	v_mov_b32_e32 v110, v2
	v_mov_b32_e32 v111, v2
	v_mov_b32_e32 v112, v2
	v_mov_b32_e32 v113, v2
	v_mov_b32_e32 v122, v2
	v_mov_b32_e32 v123, v2
	v_mov_b32_e32 v124, v2
	v_mov_b32_e32 v125, v2
	v_mov_b32_e32 v126, v2
	v_mov_b32_e32 v127, v2
	v_mov_b32_e32 v128, v2
	v_mov_b32_e32 v129, v2
	.p2align	8

.LBB0_1216:
	s_ashr_i32 s15, s14, 31
	s_lshl_b64 s[16:17], s[14:15], 15
	v_readlane_b32 s5, v245, 53
	s_add_u32 s16, s5, s16
	v_readlane_b32 s5, v245, 56
	s_addc_u32 s17, s5, s17
	s_and_b64 s[18:19], s[10:11], exec
	s_cselect_b32 s5, s17, s23
	s_cselect_b32 s15, s16, s22
	s_ashr_i32 s13, s12, 31
	s_lshl_b64 s[18:19], s[12:13], 15
	v_readlane_b32 s24, v245, 4
	v_readlane_b32 s25, v245, 5
	s_add_u32 s18, s24, s18
	s_addc_u32 s19, s25, s19
	s_and_b64 s[24:25], s[10:11], exec
	s_cselect_b32 s13, s19, s21
	s_cselect_b32 s40, s18, s20
	s_add_u32 s41, s20, 0x100000
	s_addc_u32 s42, s21, 0
	s_add_u32 s20, s22, 0x104000
	v_mov_b32_e32 v2, 0
	s_addc_u32 s21, s23, 0
	s_mov_b32 s43, -2
	v_mov_b32_e32 v3, v2
	v_mov_b32_e32 v4, v2
	v_mov_b32_e32 v5, v2
	v_mov_b32_e32 v6, v2
	s_waitcnt lgkmcnt(0)
	v_mov_b32_e32 v7, v2
	v_mov_b32_e32 v8, v2
	v_mov_b32_e32 v9, v2
	v_mov_b32_e32 v18, v2
	v_mov_b32_e32 v19, v2
	v_mov_b32_e32 v20, v2
	v_mov_b32_e32 v21, v2
	v_mov_b32_e32 v22, v2
	v_mov_b32_e32 v23, v2
	v_mov_b32_e32 v24, v2
	v_mov_b32_e32 v25, v2
	v_mov_b32_e32 v34, v2
	v_mov_b32_e32 v35, v2
	v_mov_b32_e32 v36, v2
	v_mov_b32_e32 v37, v2
	v_mov_b32_e32 v38, v2
	v_mov_b32_e32 v39, v2
	v_mov_b32_e32 v40, v2
	v_mov_b32_e32 v41, v2
	v_mov_b32_e32 v50, v2
	v_mov_b32_e32 v51, v2
	v_mov_b32_e32 v52, v2
	v_mov_b32_e32 v53, v2
	v_mov_b32_e32 v54, v2
	v_mov_b32_e32 v55, v2
	v_mov_b32_e32 v56, v2
	v_mov_b32_e32 v57, v2
	v_mov_b32_e32 v10, v2
	v_mov_b32_e32 v11, v2
	v_mov_b32_e32 v12, v2
	v_mov_b32_e32 v13, v2
	v_mov_b32_e32 v14, v2
	v_mov_b32_e32 v15, v2
	v_mov_b32_e32 v16, v2
	v_mov_b32_e32 v17, v2
	v_mov_b32_e32 v26, v2
	v_mov_b32_e32 v27, v2
	v_mov_b32_e32 v28, v2
	v_mov_b32_e32 v29, v2
	v_mov_b32_e32 v30, v2
	v_mov_b32_e32 v31, v2
	v_mov_b32_e32 v32, v2
	v_mov_b32_e32 v33, v2
	v_mov_b32_e32 v42, v2
	v_mov_b32_e32 v43, v2
	v_mov_b32_e32 v44, v2
	v_mov_b32_e32 v45, v2
	v_mov_b32_e32 v46, v2
	v_mov_b32_e32 v47, v2
	v_mov_b32_e32 v48, v2
	v_mov_b32_e32 v49, v2
	v_mov_b32_e32 v58, v2
	v_mov_b32_e32 v59, v2
	v_mov_b32_e32 v60, v2
	v_mov_b32_e32 v61, v2
	v_mov_b32_e32 v62, v2
	v_mov_b32_e32 v63, v2
	v_mov_b32_e32 v64, v2
	v_mov_b32_e32 v65, v2
	v_mov_b32_e32 v66, v2
	v_mov_b32_e32 v67, v2
	v_mov_b32_e32 v68, v2
	v_mov_b32_e32 v69, v2
	v_mov_b32_e32 v70, v2
	v_mov_b32_e32 v71, v2
	v_mov_b32_e32 v72, v2
	v_mov_b32_e32 v73, v2
	v_mov_b32_e32 v82, v2
	v_mov_b32_e32 v83, v2
	v_mov_b32_e32 v84, v2
	v_mov_b32_e32 v85, v2
	v_mov_b32_e32 v86, v2
	v_mov_b32_e32 v87, v2
	v_mov_b32_e32 v88, v2
	v_mov_b32_e32 v89, v2
	v_mov_b32_e32 v98, v2
	v_mov_b32_e32 v99, v2
	v_mov_b32_e32 v100, v2
	v_mov_b32_e32 v101, v2
	v_mov_b32_e32 v102, v2
	v_mov_b32_e32 v103, v2
	v_mov_b32_e32 v104, v2
	v_mov_b32_e32 v105, v2
	v_mov_b32_e32 v114, v2
	v_mov_b32_e32 v115, v2
	v_mov_b32_e32 v116, v2
	v_mov_b32_e32 v117, v2
	v_mov_b32_e32 v118, v2
	v_mov_b32_e32 v119, v2
	v_mov_b32_e32 v120, v2
	v_mov_b32_e32 v121, v2
	v_mov_b32_e32 v74, v2
	v_mov_b32_e32 v75, v2
	v_mov_b32_e32 v76, v2
	v_mov_b32_e32 v77, v2
	v_mov_b32_e32 v78, v2
	v_mov_b32_e32 v79, v2
	v_mov_b32_e32 v80, v2
	v_mov_b32_e32 v81, v2
	v_mov_b32_e32 v90, v2
	v_mov_b32_e32 v91, v2
	v_mov_b32_e32 v92, v2
	v_mov_b32_e32 v93, v2
	v_mov_b32_e32 v94, v2
	v_mov_b32_e32 v95, v2
	v_mov_b32_e32 v96, v2
	v_mov_b32_e32 v97, v2
	v_mov_b32_e32 v106, v2
	v_mov_b32_e32 v107, v2
	v_mov_b32_e32 v108, v2
	v_mov_b32_e32 v109, v2
	v_mov_b32_e32 v110, v2
	v_mov_b32_e32 v111, v2
	v_mov_b32_e32 v112, v2
	v_mov_b32_e32 v113, v2
	v_mov_b32_e32 v122, v2
	v_mov_b32_e32 v123, v2
	v_mov_b32_e32 v124, v2
	v_mov_b32_e32 v125, v2
	v_mov_b32_e32 v126, v2
	v_mov_b32_e32 v127, v2
	v_mov_b32_e32 v128, v2
	v_mov_b32_e32 v129, v2
	.p2align	8

.LBB0_2184:
	s_ashr_i32 s15, s14, 31
	s_lshl_b64 s[16:17], s[14:15], 15
	s_add_u32 s16, s33, s16
	s_addc_u32 s17, s58, s17
	s_and_b64 s[18:19], s[10:11], exec
	s_cselect_b32 s5, s17, s23
	s_cselect_b32 s15, s16, s22
	s_ashr_i32 s13, s12, 31
	s_lshl_b64 s[18:19], s[12:13], 15
	v_readlane_b32 s24, v245, 2
	v_readlane_b32 s25, v245, 3
	s_add_u32 s18, s24, s18
	s_addc_u32 s19, s25, s19
	s_and_b64 s[24:25], s[10:11], exec
	s_cselect_b32 s13, s19, s21
	s_cselect_b32 s41, s18, s20
	s_add_u32 s42, s20, 0x100000
	s_addc_u32 s43, s21, 0
	s_add_u32 s20, s22, 0x104000
	v_mov_b32_e32 v2, 0
	s_addc_u32 s21, s23, 0
	s_mov_b32 s44, -2
	v_mov_b32_e32 v3, v2
	v_mov_b32_e32 v4, v2
	v_mov_b32_e32 v5, v2
	v_mov_b32_e32 v6, v2
	s_waitcnt lgkmcnt(0)
	v_mov_b32_e32 v7, v2
	v_mov_b32_e32 v8, v2
	v_mov_b32_e32 v9, v2
	v_mov_b32_e32 v18, v2
	v_mov_b32_e32 v19, v2
	v_mov_b32_e32 v20, v2
	v_mov_b32_e32 v21, v2
	v_mov_b32_e32 v22, v2
	v_mov_b32_e32 v23, v2
	v_mov_b32_e32 v24, v2
	v_mov_b32_e32 v25, v2
	v_mov_b32_e32 v34, v2
	v_mov_b32_e32 v35, v2
	v_mov_b32_e32 v36, v2
	v_mov_b32_e32 v37, v2
	v_mov_b32_e32 v38, v2
	v_mov_b32_e32 v39, v2
	v_mov_b32_e32 v40, v2
	v_mov_b32_e32 v41, v2
	v_mov_b32_e32 v50, v2
	v_mov_b32_e32 v51, v2
	v_mov_b32_e32 v52, v2
	v_mov_b32_e32 v53, v2
	v_mov_b32_e32 v54, v2
	v_mov_b32_e32 v55, v2
	v_mov_b32_e32 v56, v2
	v_mov_b32_e32 v57, v2
	v_mov_b32_e32 v10, v2
	v_mov_b32_e32 v11, v2
	v_mov_b32_e32 v12, v2
	v_mov_b32_e32 v13, v2
	v_mov_b32_e32 v14, v2
	v_mov_b32_e32 v15, v2
	v_mov_b32_e32 v16, v2
	v_mov_b32_e32 v17, v2
	v_mov_b32_e32 v26, v2
	v_mov_b32_e32 v27, v2
	v_mov_b32_e32 v28, v2
	v_mov_b32_e32 v29, v2
	v_mov_b32_e32 v30, v2
	v_mov_b32_e32 v31, v2
	v_mov_b32_e32 v32, v2
	v_mov_b32_e32 v33, v2
	v_mov_b32_e32 v42, v2
	v_mov_b32_e32 v43, v2
	v_mov_b32_e32 v44, v2
	v_mov_b32_e32 v45, v2
	v_mov_b32_e32 v46, v2
	v_mov_b32_e32 v47, v2
	v_mov_b32_e32 v48, v2
	v_mov_b32_e32 v49, v2
	v_mov_b32_e32 v58, v2
	v_mov_b32_e32 v59, v2
	v_mov_b32_e32 v60, v2
	v_mov_b32_e32 v61, v2
	v_mov_b32_e32 v62, v2
	v_mov_b32_e32 v63, v2
	v_mov_b32_e32 v64, v2
	v_mov_b32_e32 v65, v2
	v_mov_b32_e32 v66, v2
	v_mov_b32_e32 v67, v2
	v_mov_b32_e32 v68, v2
	v_mov_b32_e32 v69, v2
	v_mov_b32_e32 v70, v2
	v_mov_b32_e32 v71, v2
	v_mov_b32_e32 v72, v2
	v_mov_b32_e32 v73, v2
	v_mov_b32_e32 v82, v2
	v_mov_b32_e32 v83, v2
	v_mov_b32_e32 v84, v2
	v_mov_b32_e32 v85, v2
	v_mov_b32_e32 v86, v2
	v_mov_b32_e32 v87, v2
	v_mov_b32_e32 v88, v2
	v_mov_b32_e32 v89, v2
	v_mov_b32_e32 v98, v2
	v_mov_b32_e32 v99, v2
	v_mov_b32_e32 v100, v2
	v_mov_b32_e32 v101, v2
	v_mov_b32_e32 v102, v2
	v_mov_b32_e32 v103, v2
	v_mov_b32_e32 v104, v2
	v_mov_b32_e32 v105, v2
	v_mov_b32_e32 v114, v2
	v_mov_b32_e32 v115, v2
	v_mov_b32_e32 v116, v2
	v_mov_b32_e32 v117, v2
	v_mov_b32_e32 v118, v2
	v_mov_b32_e32 v119, v2
	v_mov_b32_e32 v120, v2
	v_mov_b32_e32 v121, v2
	v_mov_b32_e32 v74, v2
	v_mov_b32_e32 v75, v2
	v_mov_b32_e32 v76, v2
	v_mov_b32_e32 v77, v2
	v_mov_b32_e32 v78, v2
	v_mov_b32_e32 v79, v2
	v_mov_b32_e32 v80, v2
	v_mov_b32_e32 v81, v2
	v_mov_b32_e32 v90, v2
	v_mov_b32_e32 v91, v2
	v_mov_b32_e32 v92, v2
	v_mov_b32_e32 v93, v2
	v_mov_b32_e32 v94, v2
	v_mov_b32_e32 v95, v2
	v_mov_b32_e32 v96, v2
	v_mov_b32_e32 v97, v2
	v_mov_b32_e32 v106, v2
	v_mov_b32_e32 v107, v2
	v_mov_b32_e32 v108, v2
	v_mov_b32_e32 v109, v2
	v_mov_b32_e32 v110, v2
	v_mov_b32_e32 v111, v2
	v_mov_b32_e32 v112, v2
	v_mov_b32_e32 v113, v2
	v_mov_b32_e32 v122, v2
	v_mov_b32_e32 v123, v2
	v_mov_b32_e32 v124, v2
	v_mov_b32_e32 v125, v2
	v_mov_b32_e32 v126, v2
	v_mov_b32_e32 v127, v2
	v_mov_b32_e32 v128, v2
	v_mov_b32_e32 v129, v2
	.p2align	8

.LBB0_2479:
	s_ashr_i32 s17, s16, 31
	s_lshl_b64 s[18:19], s[16:17], 15
	s_add_u32 s18, s1, s18
	s_addc_u32 s19, s13, s19
	s_and_b64 s[20:21], s[10:11], exec
	s_cselect_b32 s5, s19, s27
	s_cselect_b32 s17, s18, s26
	s_ashr_i32 s15, s14, 31
	s_lshl_b64 s[20:21], s[14:15], 15
	v_readlane_b32 s28, v245, 10
	v_readlane_b32 s29, v245, 11
	s_add_u32 s20, s28, s20
	s_addc_u32 s21, s29, s21
	s_and_b64 s[28:29], s[10:11], exec
	s_cselect_b32 s15, s21, s25
	s_cselect_b32 s23, s20, s24
	s_add_u32 s46, s24, 0x700000
	s_addc_u32 s47, s25, 0
	s_add_u32 s24, s26, 0x104000
	v_mov_b32_e32 v34, 0
	s_addc_u32 s25, s27, 0
	s_mov_b32 s48, -2
	v_mov_b32_e32 v35, v34
	v_mov_b32_e32 v36, v34
	v_mov_b32_e32 v37, v34
	v_mov_b32_e32 v38, v34
	v_mov_b32_e32 v39, v34
	v_mov_b32_e32 v40, v34
	v_mov_b32_e32 v41, v34
	v_mov_b32_e32 v50, v34
	v_mov_b32_e32 v51, v34
	v_mov_b32_e32 v52, v34
	v_mov_b32_e32 v53, v34
	v_mov_b32_e32 v54, v34
	v_mov_b32_e32 v55, v34
	v_mov_b32_e32 v56, v34
	v_mov_b32_e32 v57, v34
	v_mov_b32_e32 v66, v34
	v_mov_b32_e32 v67, v34
	v_mov_b32_e32 v68, v34
	v_mov_b32_e32 v69, v34
	v_mov_b32_e32 v70, v34
	v_mov_b32_e32 v71, v34
	v_mov_b32_e32 v72, v34
	v_mov_b32_e32 v73, v34
	v_mov_b32_e32 v82, v34
	v_mov_b32_e32 v83, v34
	v_mov_b32_e32 v84, v34
	v_mov_b32_e32 v85, v34
	v_mov_b32_e32 v86, v34
	v_mov_b32_e32 v87, v34
	v_mov_b32_e32 v88, v34
	v_mov_b32_e32 v89, v34
	v_mov_b32_e32 v42, v34
	v_mov_b32_e32 v43, v34
	v_mov_b32_e32 v44, v34
	v_mov_b32_e32 v45, v34
	v_mov_b32_e32 v46, v34
	v_mov_b32_e32 v47, v34
	v_mov_b32_e32 v48, v34
	v_mov_b32_e32 v49, v34
	v_mov_b32_e32 v58, v34
	v_mov_b32_e32 v59, v34
	v_mov_b32_e32 v60, v34
	v_mov_b32_e32 v61, v34
	v_mov_b32_e32 v62, v34
	v_mov_b32_e32 v63, v34
	v_mov_b32_e32 v64, v34
	v_mov_b32_e32 v65, v34
	v_mov_b32_e32 v74, v34
	v_mov_b32_e32 v75, v34
	v_mov_b32_e32 v76, v34
	v_mov_b32_e32 v77, v34
	v_mov_b32_e32 v78, v34
	v_mov_b32_e32 v79, v34
	v_mov_b32_e32 v80, v34
	v_mov_b32_e32 v81, v34
	v_mov_b32_e32 v90, v34
	v_mov_b32_e32 v91, v34
	v_mov_b32_e32 v92, v34
	v_mov_b32_e32 v93, v34
	v_mov_b32_e32 v94, v34
	v_mov_b32_e32 v95, v34
	v_mov_b32_e32 v96, v34
	v_mov_b32_e32 v97, v34
	v_mov_b32_e32 v98, v34
	v_mov_b32_e32 v99, v34
	v_mov_b32_e32 v100, v34
	v_mov_b32_e32 v101, v34
	v_mov_b32_e32 v102, v34
	v_mov_b32_e32 v103, v34
	v_mov_b32_e32 v104, v34
	v_mov_b32_e32 v105, v34
	v_mov_b32_e32 v114, v34
	v_mov_b32_e32 v115, v34
	v_mov_b32_e32 v116, v34
	v_mov_b32_e32 v117, v34
	v_mov_b32_e32 v118, v34
	v_mov_b32_e32 v119, v34
	v_mov_b32_e32 v120, v34
	v_mov_b32_e32 v121, v34
	v_mov_b32_e32 v130, v34
	v_mov_b32_e32 v131, v34
	v_mov_b32_e32 v132, v34
	v_mov_b32_e32 v133, v34
	v_mov_b32_e32 v134, v34
	v_mov_b32_e32 v135, v34
	v_mov_b32_e32 v136, v34
	v_mov_b32_e32 v137, v34
	v_mov_b32_e32 v146, v34
	v_mov_b32_e32 v147, v34
	v_mov_b32_e32 v148, v34
	v_mov_b32_e32 v149, v34
	v_mov_b32_e32 v150, v34
	v_mov_b32_e32 v151, v34
	v_mov_b32_e32 v152, v34
	v_mov_b32_e32 v153, v34
	v_mov_b32_e32 v106, v34
	v_mov_b32_e32 v107, v34
	v_mov_b32_e32 v108, v34
	v_mov_b32_e32 v109, v34
	v_mov_b32_e32 v110, v34
	v_mov_b32_e32 v111, v34
	v_mov_b32_e32 v112, v34
	v_mov_b32_e32 v113, v34
	v_mov_b32_e32 v122, v34
	v_mov_b32_e32 v123, v34
	v_mov_b32_e32 v124, v34
	v_mov_b32_e32 v125, v34
	v_mov_b32_e32 v126, v34
	v_mov_b32_e32 v127, v34
	v_mov_b32_e32 v128, v34
	v_mov_b32_e32 v129, v34
	v_mov_b32_e32 v138, v34
	v_mov_b32_e32 v139, v34
	v_mov_b32_e32 v140, v34
	v_mov_b32_e32 v141, v34
	v_mov_b32_e32 v142, v34
	v_mov_b32_e32 v143, v34
	v_mov_b32_e32 v144, v34
	v_mov_b32_e32 v145, v34
	v_mov_b32_e32 v154, v34
	v_mov_b32_e32 v155, v34
	v_mov_b32_e32 v156, v34
	v_mov_b32_e32 v157, v34
	v_mov_b32_e32 v158, v34
	v_mov_b32_e32 v159, v34
	v_mov_b32_e32 v160, v34
	v_mov_b32_e32 v161, v34
	.p2align	8

.LBB0_2713:
	s_ashr_i32 s17, s16, 31
	s_lshl_b64 s[18:19], s[16:17], 15
	v_readlane_b32 s20, v245, 14
	v_readlane_b32 s21, v245, 15
	s_add_u32 s18, s20, s18
	s_addc_u32 s19, s21, s19
	s_and_b64 s[20:21], s[8:9], exec
	s_cselect_b32 s5, s19, s25
	s_cselect_b32 s17, s18, s24
	s_ashr_i32 s15, s14, 31
	s_lshl_b64 s[20:21], s[14:15], 15
	s_add_u32 s20, s88, s20
	s_addc_u32 s21, s89, s21
	s_and_b64 s[26:27], s[8:9], exec
	s_cselect_b32 s15, s21, s23
	s_cselect_b32 s41, s20, s22
	s_add_u32 s42, s22, 0x100000
	s_addc_u32 s43, s23, 0
	s_add_u32 s22, s24, 0x104000
	v_mov_b32_e32 v34, 0
	s_addc_u32 s23, s25, 0
	s_mov_b32 s44, -2
	v_mov_b32_e32 v35, v34
	v_mov_b32_e32 v36, v34
	v_mov_b32_e32 v37, v34
	v_mov_b32_e32 v38, v34
	v_mov_b32_e32 v39, v34
	v_mov_b32_e32 v40, v34
	v_mov_b32_e32 v41, v34
	v_mov_b32_e32 v50, v34
	v_mov_b32_e32 v51, v34
	v_mov_b32_e32 v52, v34
	v_mov_b32_e32 v53, v34
	v_mov_b32_e32 v54, v34
	v_mov_b32_e32 v55, v34
	v_mov_b32_e32 v56, v34
	v_mov_b32_e32 v57, v34
	v_mov_b32_e32 v66, v34
	v_mov_b32_e32 v67, v34
	v_mov_b32_e32 v68, v34
	v_mov_b32_e32 v69, v34
	v_mov_b32_e32 v70, v34
	v_mov_b32_e32 v71, v34
	v_mov_b32_e32 v72, v34
	v_mov_b32_e32 v73, v34
	v_mov_b32_e32 v82, v34
	v_mov_b32_e32 v83, v34
	v_mov_b32_e32 v84, v34
	v_mov_b32_e32 v85, v34
	v_mov_b32_e32 v86, v34
	v_mov_b32_e32 v87, v34
	v_mov_b32_e32 v88, v34
	v_mov_b32_e32 v89, v34
	v_mov_b32_e32 v42, v34
	v_mov_b32_e32 v43, v34
	v_mov_b32_e32 v44, v34
	v_mov_b32_e32 v45, v34
	v_mov_b32_e32 v46, v34
	v_mov_b32_e32 v47, v34
	v_mov_b32_e32 v48, v34
	v_mov_b32_e32 v49, v34
	v_mov_b32_e32 v58, v34
	v_mov_b32_e32 v59, v34
	v_mov_b32_e32 v60, v34
	v_mov_b32_e32 v61, v34
	v_mov_b32_e32 v62, v34
	v_mov_b32_e32 v63, v34
	v_mov_b32_e32 v64, v34
	v_mov_b32_e32 v65, v34
	v_mov_b32_e32 v74, v34
	v_mov_b32_e32 v75, v34
	v_mov_b32_e32 v76, v34
	v_mov_b32_e32 v77, v34
	v_mov_b32_e32 v78, v34
	v_mov_b32_e32 v79, v34
	v_mov_b32_e32 v80, v34
	v_mov_b32_e32 v81, v34
	v_mov_b32_e32 v90, v34
	v_mov_b32_e32 v91, v34
	v_mov_b32_e32 v92, v34
	v_mov_b32_e32 v93, v34
	v_mov_b32_e32 v94, v34
	v_mov_b32_e32 v95, v34
	v_mov_b32_e32 v96, v34
	v_mov_b32_e32 v97, v34
	v_mov_b32_e32 v98, v34
	v_mov_b32_e32 v99, v34
	v_mov_b32_e32 v100, v34
	v_mov_b32_e32 v101, v34
	v_mov_b32_e32 v102, v34
	v_mov_b32_e32 v103, v34
	v_mov_b32_e32 v104, v34
	v_mov_b32_e32 v105, v34
	v_mov_b32_e32 v114, v34
	v_mov_b32_e32 v115, v34
	v_mov_b32_e32 v116, v34
	v_mov_b32_e32 v117, v34
	v_mov_b32_e32 v118, v34
	v_mov_b32_e32 v119, v34
	v_mov_b32_e32 v120, v34
	v_mov_b32_e32 v121, v34
	v_mov_b32_e32 v130, v34
	v_mov_b32_e32 v131, v34
	v_mov_b32_e32 v132, v34
	v_mov_b32_e32 v133, v34
	v_mov_b32_e32 v134, v34
	v_mov_b32_e32 v135, v34
	v_mov_b32_e32 v136, v34
	v_mov_b32_e32 v137, v34
	v_mov_b32_e32 v146, v34
	v_mov_b32_e32 v147, v34
	v_mov_b32_e32 v148, v34
	v_mov_b32_e32 v149, v34
	v_mov_b32_e32 v150, v34
	v_mov_b32_e32 v151, v34
	v_mov_b32_e32 v152, v34
	v_mov_b32_e32 v153, v34
	v_mov_b32_e32 v106, v34
	v_mov_b32_e32 v107, v34
	v_mov_b32_e32 v108, v34
	v_mov_b32_e32 v109, v34
	v_mov_b32_e32 v110, v34
	v_mov_b32_e32 v111, v34
	v_mov_b32_e32 v112, v34
	v_mov_b32_e32 v113, v34
	v_mov_b32_e32 v122, v34
	v_mov_b32_e32 v123, v34
	v_mov_b32_e32 v124, v34
	v_mov_b32_e32 v125, v34
	v_mov_b32_e32 v126, v34
	v_mov_b32_e32 v127, v34
	v_mov_b32_e32 v128, v34
	v_mov_b32_e32 v129, v34
	v_mov_b32_e32 v138, v34
	v_mov_b32_e32 v139, v34
	v_mov_b32_e32 v140, v34
	v_mov_b32_e32 v141, v34
	v_mov_b32_e32 v142, v34
	v_mov_b32_e32 v143, v34
	v_mov_b32_e32 v144, v34
	v_mov_b32_e32 v145, v34
	v_mov_b32_e32 v154, v34
	v_mov_b32_e32 v155, v34
	v_mov_b32_e32 v156, v34
	v_mov_b32_e32 v157, v34
	v_mov_b32_e32 v158, v34
	v_mov_b32_e32 v159, v34
	v_mov_b32_e32 v160, v34
	v_mov_b32_e32 v161, v34
	.p2align	8
